# MLA fast path v2: softmax scale folded into q-up weights, MFMA accumulator starts at -m_ref, lazy reference max with exact fallback, packed row sums
# speedup vs baseline: 1.0195x; 1.0195x over previous
.LBB0_46:
	s_lshl_b32 s17, s8, 1
	s_lshl_b32 s18, s9, 1
	v_or_b32_e32 v4, s17, v1
	v_or_b32_e32 v92, s18, v2
	s_add_i32 s19, s17, 4
	s_add_i32 s20, s18, 4
	s_add_i32 s21, s17, 8
	s_add_i32 s23, s18, 8
	s_add_i32 s30, s17, 12
	s_add_i32 s31, s18, 12
	s_add_i32 s33, s17, 16
	s_add_i32 s34, s18, 16
	s_add_i32 s35, s17, 20
	s_add_i32 s36, s18, 20
	s_add_i32 s37, s17, 24
	s_add_i32 s38, s18, 24
	s_add_i32 s17, s17, 28
	s_add_i32 s18, s18, 28
	v_add_u32_e32 v60, s7, v92
	v_or_b32_e32 v93, s19, v1
	v_or_b32_e32 v94, s20, v2
	v_or_b32_e32 v95, s21, v1
	v_or_b32_e32 v96, s23, v2
	v_or_b32_e32 v97, s30, v1
	v_or_b32_e32 v98, s31, v2
	v_or_b32_e32 v99, s33, v1
	v_or_b32_e32 v100, s34, v2
	v_or_b32_e32 v101, s35, v1
	v_or_b32_e32 v102, s36, v2
	v_or_b32_e32 v103, s37, v1
	v_or_b32_e32 v104, s38, v2
	v_or_b32_e32 v105, s17, v1
	v_or_b32_e32 v106, s18, v2
	v_add_u32_e32 v62, s4, v4
	v_mad_u64_u32 v[60:61], s[18:19], v60, s12, v[54:55]
	v_add_u32_e32 v66, s4, v93
	v_add_u32_e32 v64, s7, v94
	v_add_u32_e32 v70, s4, v95
	v_add_u32_e32 v68, s7, v96
	v_add_u32_e32 v74, s4, v97
	v_add_u32_e32 v72, s7, v98
	v_add_u32_e32 v78, s4, v99
	v_add_u32_e32 v76, s7, v100
	v_add_u32_e32 v82, s4, v101
	v_add_u32_e32 v80, s7, v102
	v_add_u32_e32 v86, s4, v103
	v_add_u32_e32 v84, s7, v104
	v_add_u32_e32 v90, s4, v105
	v_add_u32_e32 v88, s7, v106
	v_mad_u64_u32 v[62:63], s[18:19], v62, s12, v[54:55]
	v_mad_u64_u32 v[64:65], s[18:19], v64, s12, v[54:55]
	v_mad_u64_u32 v[66:67], s[18:19], v66, s12, v[54:55]
	v_mad_u64_u32 v[68:69], s[18:19], v68, s12, v[54:55]
	v_mad_u64_u32 v[70:71], s[18:19], v70, s12, v[54:55]
	v_mad_u64_u32 v[72:73], s[18:19], v72, s12, v[54:55]
	v_mad_u64_u32 v[74:75], s[18:19], v74, s12, v[54:55]
	v_mad_u64_u32 v[76:77], s[18:19], v76, s12, v[54:55]
	v_mad_u64_u32 v[78:79], s[18:19], v78, s12, v[54:55]
	v_mad_u64_u32 v[80:81], s[18:19], v80, s12, v[54:55]
	v_mad_u64_u32 v[82:83], s[18:19], v82, s12, v[54:55]
	v_mad_u64_u32 v[84:85], s[18:19], v84, s12, v[54:55]
	v_mad_u64_u32 v[86:87], s[18:19], v86, s12, v[54:55]
	v_mad_u64_u32 v[88:89], s[18:19], v88, s12, v[54:55]
	v_mad_u64_u32 v[90:91], s[18:19], v90, s12, v[54:55]
	global_load_dword v107, v[60:61], off
	global_load_dword v108, v[62:63], off
	global_load_dword v109, v[64:65], off
	global_load_dword v110, v[66:67], off
	global_load_dword v111, v[68:69], off
	global_load_dword v112, v[70:71], off
	global_load_dword v113, v[72:73], off
	global_load_dword v114, v[74:75], off
	global_load_dword v115, v[76:77], off
	global_load_dword v116, v[78:79], off
	global_load_dword v117, v[80:81], off
	global_load_dword v118, v[82:83], off
	global_load_dword v119, v[84:85], off
	global_load_dword v120, v[86:87], off
	global_load_dword v121, v[88:89], off
	global_load_dword v122, v[90:91], off
	s_add_i32 s9, s9, 16
	s_add_i32 s8, s8, 16
	s_add_i32 s16, s16, -16
	v_mad_u64_u32 v[60:61], s[18:19], v92, s10, v[10:11]
	s_cmp_lg_u32 s16, 0
	v_mad_u64_u32 v[62:63], s[18:19], v4, s10, v[10:11]
	v_mad_u64_u32 v[64:65], s[18:19], v94, s10, v[10:11]
	v_mad_u64_u32 v[66:67], s[18:19], v93, s10, v[10:11]
	v_mad_u64_u32 v[68:69], s[18:19], v96, s10, v[10:11]
	v_mad_u64_u32 v[70:71], s[18:19], v95, s10, v[10:11]
	v_mad_u64_u32 v[72:73], s[18:19], v98, s10, v[10:11]
	v_mad_u64_u32 v[74:75], s[18:19], v97, s10, v[10:11]
	v_mad_u64_u32 v[76:77], s[18:19], v100, s10, v[10:11]
	v_mad_u64_u32 v[78:79], s[18:19], v99, s10, v[10:11]
	v_mad_u64_u32 v[80:81], s[18:19], v102, s10, v[10:11]
	v_mad_u64_u32 v[82:83], s[18:19], v101, s10, v[10:11]
	v_mad_u64_u32 v[84:85], s[18:19], v104, s10, v[10:11]
	v_mad_u64_u32 v[86:87], s[18:19], v103, s10, v[10:11]
	v_mad_u64_u32 v[88:89], s[18:19], v106, s10, v[10:11]
	v_mad_u64_u32 v[90:91], s[18:19], v105, s10, v[10:11]
	s_waitcnt vmcnt(15)
	ds_write_b32 v60, v107
	s_waitcnt vmcnt(14)
	ds_write_b32 v62, v108
	s_waitcnt vmcnt(13)
	ds_write_b32 v64, v109
	s_waitcnt vmcnt(12)
	ds_write_b32 v66, v110
	s_waitcnt vmcnt(11)
	ds_write_b32 v68, v111
	s_waitcnt vmcnt(10)
	ds_write_b32 v70, v112
	s_waitcnt vmcnt(9)
	ds_write_b32 v72, v113
	s_waitcnt vmcnt(8)
	ds_write_b32 v74, v114
	s_waitcnt vmcnt(7)
	ds_write_b32 v76, v115
	s_waitcnt vmcnt(6)
	ds_write_b32 v78, v116
	s_waitcnt vmcnt(5)
	ds_write_b32 v80, v117
	s_waitcnt vmcnt(4)
	ds_write_b32 v82, v118
	s_waitcnt vmcnt(3)
	ds_write_b32 v84, v119
	s_waitcnt vmcnt(2)
	ds_write_b32 v86, v120
	s_waitcnt vmcnt(1)
	ds_write_b32 v88, v121
	s_waitcnt vmcnt(0)
	ds_write_b32 v90, v122
	s_cbranch_scc1 .LBB0_46
	s_waitcnt lgkmcnt(0)
	ds_read2_b32 v[54:55], v56 offset0:33 offset1:41
	ds_read2_b32 v[64:65], v56 offset1:8
	ds_read2_b32 v[66:67], v56 offset0:66 offset1:74
	ds_read2_b32 v[68:69], v56 offset0:99 offset1:107
	ds_read2_b32 v[70:71], v56 offset0:132 offset1:140
	ds_read2_b32 v[72:73], v56 offset0:165 offset1:173
	ds_read2_b32 v[74:75], v56 offset0:198 offset1:206
	ds_read2_b32 v[76:77], v56 offset0:231 offset1:239
	v_or_b32_e32 v4, s6, v3
	s_lshl_b32 s4, s7, 1
	v_mul_u32_u24_e32 v4, 0x180, v4
	v_lshl_add_u64 v[78:79], v[30:31], 0, s[4:5]
	v_lshlrev_b32_e32 v4, 1, v4
	v_lshl_add_u64 v[80:81], v[78:79], 0, v[4:5]
	v_or_b32_e32 v4, s6, v57
	s_waitcnt lgkmcnt(6)
	v_mul_f32_e32 v64, 0x3e16c740, v64
	v_mul_f32_e32 v54, 0x3e16c740, v54
	v_cvt_pk_bf16_f32 v60, v64, v54
	s_waitcnt lgkmcnt(4)
	v_mul_f32_e32 v66, 0x3e16c740, v66
	v_mul_f32_e32 v68, 0x3e16c740, v68
	v_cvt_pk_bf16_f32 v61, v66, v68
	s_waitcnt lgkmcnt(2)
	v_mul_f32_e32 v70, 0x3e16c740, v70
	v_mul_f32_e32 v72, 0x3e16c740, v72
	v_cvt_pk_bf16_f32 v62, v70, v72
	s_waitcnt lgkmcnt(0)
	v_mul_f32_e32 v74, 0x3e16c740, v74
	v_mul_f32_e32 v76, 0x3e16c740, v76
	v_cvt_pk_bf16_f32 v63, v74, v76
	v_mul_u32_u24_e32 v4, 0x180, v4
	global_store_dwordx4 v[80:81], v[60:63], off
	v_lshlrev_b32_e32 v4, 1, v4
	s_nop 0
	v_mul_f32_e32 v65, 0x3e16c740, v65
	v_mul_f32_e32 v55, 0x3e16c740, v55
	v_cvt_pk_bf16_f32 v60, v65, v55
	v_mul_f32_e32 v67, 0x3e16c740, v67
	v_mul_f32_e32 v69, 0x3e16c740, v69
	v_cvt_pk_bf16_f32 v61, v67, v69
	v_mul_f32_e32 v71, 0x3e16c740, v71
	v_mul_f32_e32 v73, 0x3e16c740, v73
	v_cvt_pk_bf16_f32 v62, v71, v73
	v_mul_f32_e32 v75, 0x3e16c740, v75
	v_mul_f32_e32 v77, 0x3e16c740, v77
	v_cvt_pk_bf16_f32 v63, v75, v77
	v_lshl_add_u64 v[54:55], v[78:79], 0, v[4:5]
	ds_read2_b32 v[64:65], v56 offset0:16 offset1:24
	ds_read2_b32 v[66:67], v56 offset0:49 offset1:57
	ds_read2_b32 v[68:69], v56 offset0:82 offset1:90
	ds_read2_b32 v[70:71], v56 offset0:115 offset1:123
	ds_read2_b32 v[72:73], v56 offset0:148 offset1:156
	ds_read2_b32 v[74:75], v56 offset0:181 offset1:189
	ds_read2_b32 v[76:77], v56 offset0:214 offset1:222
	ds_read2_b32 v[80:81], v56 offset0:247 offset1:255
	v_or_b32_e32 v4, s6, v58
	v_mul_u32_u24_e32 v4, 0x180, v4
	v_lshlrev_b32_e32 v4, 1, v4
	global_store_dwordx4 v[54:55], v[60:63], off
	v_lshl_add_u64 v[54:55], v[78:79], 0, v[4:5]
	v_or_b32_e32 v4, s6, v59
	v_mul_u32_u24_e32 v4, 0x180, v4
	s_waitcnt lgkmcnt(6)
	v_mul_f32_e32 v64, 0x3e16c740, v64
	v_mul_f32_e32 v66, 0x3e16c740, v66
	v_cvt_pk_bf16_f32 v60, v64, v66
	s_waitcnt lgkmcnt(4)
	v_mul_f32_e32 v68, 0x3e16c740, v68
	v_mul_f32_e32 v70, 0x3e16c740, v70
	v_cvt_pk_bf16_f32 v61, v68, v70
	s_waitcnt lgkmcnt(2)
	v_mul_f32_e32 v72, 0x3e16c740, v72
	v_mul_f32_e32 v74, 0x3e16c740, v74
	v_cvt_pk_bf16_f32 v62, v72, v74
	s_waitcnt lgkmcnt(0)
	v_mul_f32_e32 v76, 0x3e16c740, v76
	v_mul_f32_e32 v80, 0x3e16c740, v80
	v_cvt_pk_bf16_f32 v63, v76, v80
	v_lshlrev_b32_e32 v4, 1, v4
	global_store_dwordx4 v[54:55], v[60:63], off
	v_lshl_add_u64 v[54:55], v[78:79], 0, v[4:5]
	s_nop 0
	v_mul_f32_e32 v65, 0x3e16c740, v65
	v_mul_f32_e32 v67, 0x3e16c740, v67
	v_cvt_pk_bf16_f32 v60, v65, v67
	v_mul_f32_e32 v69, 0x3e16c740, v69
	v_mul_f32_e32 v71, 0x3e16c740, v71
	v_cvt_pk_bf16_f32 v61, v69, v71
	v_mul_f32_e32 v73, 0x3e16c740, v73
	v_mul_f32_e32 v75, 0x3e16c740, v75
	v_cvt_pk_bf16_f32 v62, v73, v75
	v_mul_f32_e32 v77, 0x3e16c740, v77
	v_mul_f32_e32 v81, 0x3e16c740, v81
	v_cvt_pk_bf16_f32 v63, v77, v81
	global_store_dwordx4 v[54:55], v[60:63], off
	s_waitcnt lgkmcnt(0)

.LBB0_546:
	s_or_b64 exec, exec, s[2:3]
	s_mov_b32 s23, s95
	s_mov_b64 s[74:75], s[66:67]
	s_waitcnt lgkmcnt(0)
	s_barrier
	s_cmpk_gt_i32 s23, 0x1ff
	s_cbranch_scc1 .LBB0_649
	s_cmpk_eq_i32 s72, 0x100
	s_cselect_b64 s[80:81], -1, 0
	s_lshl_b32 s0, s23, 2
	s_and_b32 s0, s0, 28
	s_ashr_i32 s1, s23, 7
	s_add_i32 s0, s0, s1
	s_bfe_u32 s1, s23, 0x40003
	s_lshl_b32 s0, s0, 4
	s_or_b32 s44, s0, s1
	s_add_u32 s45, s26, 0x17030000
	s_addc_u32 s46, s27, 0
	s_mov_b32 s47, 0
	v_mov_b32_e32 v1, 0
	v_mov_b32_e32 v160, 0xfffffb00
	s_movk_i32 s48, 0x2ff
	s_mov_b32 s49, 0x2aaaaaab
	s_movk_i32 s50, 0x600
	s_movk_i32 s51, 0xd0
	s_mov_b32 s62, 0xff800000
	s_mov_b32 s63, 1.0
	v_mov_b32_e32 v161, 0x5400
	v_mov_b32_e32 v162, 0xff800000
	v_mbcnt_hi_u32_b32 v163, -1, v239
	s_mov_b32 s64, s23
	s_branch .LBB0_549

.LBB0_616:
	s_cmp_lt_i32 s19, 0x80
	s_cbranch_scc1 .Lmla_nofast_l0
	s_add_i32 s0, s19, 64
	s_cmp_le_i32 s0, s67
	s_cbranch_scc1 .Lmla_fast_l0
.Lmla_nofast_l0:
	s_mov_b32 s98, 0
	s_mul_i32 s1, s18, 0xa800
	s_add_i32 s1, s1, 0
	s_sub_i32 s0, s19, 63
	v_add_u32_e32 v0, s1, v183
	s_cmp_le_i32 s0, s69
	v_add3_u32 v14, s1, v148, v191
	v_add3_u32 v0, v0, v184, v185
	s_cbranch_scc0 .LBB0_623
.Lmla_orig0_l0:
	ds_read_b128 v[2:5], v14
	ds_read_b128 v[6:9], v14 offset:32
	ds_read_b128 v[10:13], v14 offset:64
	ds_read_b128 v[48:51], v14 offset:96
	ds_read_b128 v[52:55], v14 offset:128
	ds_read_b128 v[56:59], v14 offset:160
	ds_read_b128 v[60:63], v14 offset:6656
	ds_read_b128 v[124:127], v14 offset:6688
	ds_read_b128 v[128:131], v14 offset:6720
	ds_read_b128 v[132:135], v14 offset:6752
	ds_read_b128 v[136:139], v14 offset:6784
	ds_read_b128 v[140:143], v14 offset:6816
	s_waitcnt lgkmcnt(11)
	v_mfma_f32_32x32x16_bf16 v[64:79], v[2:5], v[92:95], 0
	s_waitcnt lgkmcnt(10)
	v_mfma_f32_32x32x16_bf16 v[64:79], v[6:9], v[96:99], v[64:79]
	s_waitcnt lgkmcnt(9)
	v_mfma_f32_32x32x16_bf16 v[64:79], v[10:13], v[100:103], v[64:79]
	s_waitcnt lgkmcnt(8)
	v_mfma_f32_32x32x16_bf16 v[64:79], v[48:51], v[104:107], v[64:79]
	s_waitcnt lgkmcnt(7)
	v_mfma_f32_32x32x16_bf16 v[64:79], v[52:55], v[116:119], v[64:79]
	s_waitcnt lgkmcnt(6)
	v_mfma_f32_32x32x16_bf16 v[64:79], v[56:59], v[120:123], v[64:79]
	s_waitcnt lgkmcnt(5)
	v_mfma_f32_32x32x16_bf16 v[48:63], v[60:63], v[92:95], 0
	s_waitcnt lgkmcnt(4)
	v_mfma_f32_32x32x16_bf16 v[48:63], v[124:127], v[96:99], v[48:63]
	s_waitcnt lgkmcnt(3)
	v_mfma_f32_32x32x16_bf16 v[48:63], v[128:131], v[100:103], v[48:63]
	s_waitcnt lgkmcnt(2)
	v_mfma_f32_32x32x16_bf16 v[48:63], v[132:135], v[104:107], v[48:63]
	s_waitcnt lgkmcnt(1)
	v_mfma_f32_32x32x16_bf16 v[48:63], v[136:139], v[116:119], v[48:63]
	s_waitcnt lgkmcnt(0)
	v_mfma_f32_32x32x16_bf16 v[48:63], v[140:143], v[120:123], v[48:63]
	ds_read_b64_tr_b16 v[140:141], v0 offset:13312
	ds_read_b64_tr_b16 v[142:143], v0 offset:13824
	ds_read_b64_tr_b16 v[136:137], v0 offset:14336
	ds_read_b64_tr_b16 v[138:139], v0 offset:14848
	ds_read_b64_tr_b16 v[132:133], v0 offset:15360
	ds_read_b64_tr_b16 v[134:135], v0 offset:15872
	ds_read_b64_tr_b16 v[128:129], v0 offset:16384
	ds_read_b64_tr_b16 v[130:131], v0 offset:16896
	ds_read_b64_tr_b16 v[124:125], v0 offset:17408
	ds_read_b64_tr_b16 v[126:127], v0 offset:17920
	ds_read_b64_tr_b16 v[10:11], v0 offset:18432
	ds_read_b64_tr_b16 v[12:13], v0 offset:18944
	ds_read_b64_tr_b16 v[6:7], v0 offset:19456
	ds_read_b64_tr_b16 v[8:9], v0 offset:19968
	ds_read_b64_tr_b16 v[2:3], v0 offset:20480
	ds_read_b64_tr_b16 v[4:5], v0 offset:20992
	s_cmp_gt_i32 s19, s67
	s_mov_b64 s[16:17], -1
	s_cbranch_scc1 .LBB0_619
	v_max3_f32 v15, v64, s62, v65
	v_max3_f32 v15, v15, v66, v67
	v_max3_f32 v15, v15, v68, v69
	v_max3_f32 v15, v15, v70, v71
	v_max3_f32 v15, v15, v72, v73
	v_max3_f32 v15, v15, v74, v75
	v_max3_f32 v15, v15, v76, v77
	v_max3_f32 v15, v15, v78, v79
	v_max3_f32 v15, v15, v48, v49
	v_max3_f32 v15, v15, v50, v51
	v_max3_f32 v15, v15, v52, v53
	v_max3_f32 v15, v15, v54, v55
	v_max3_f32 v15, v15, v56, v57
	v_max3_f32 v15, v15, v58, v59
	v_max3_f32 v15, v15, v60, v61
	v_max3_f32 v15, v15, v62, v63
	s_mov_b64 s[16:17], 0

.LBB0_621:
	v_and_b32_e32 v203, 64, v163
	v_xor_b32_e32 v202, 32, v163
	v_add_u32_e32 v203, 64, v203
	v_cmp_lt_i32_e32 vcc, v202, v203
	v_max_f32_e32 v203, v201, v201
	s_nop 0
	v_cndmask_b32_e32 v202, v163, v202, vcc
	v_lshlrev_b32_e32 v202, 2, v202
	ds_bpermute_b32 v202, v202, v15
	v_max_f32_e32 v15, v15, v15
	s_waitcnt lgkmcnt(0)
	v_max_f32_e32 v202, v202, v202
	v_max_f32_e32 v15, v15, v202
	v_mul_f32_e32 v15, 1.0, v15
	v_max_f32_e32 v15, v203, v15
	v_cmp_neq_f32_e32 vcc, s62, v15
	s_nop 1
	v_cndmask_b32_e32 v202, 0, v15, vcc
	v_fma_f32 v64, v64, s63, -v202
	v_exp_f32_e32 v203, v64
	v_fma_f32 v64, v65, s63, -v202
	v_exp_f32_e32 v65, v64
	v_fma_f32 v64, v66, s63, -v202
	v_exp_f32_e32 v66, v64
	v_fma_f32 v64, v67, s63, -v202
	v_exp_f32_e32 v67, v64
	v_fma_f32 v68, v68, s63, -v202
	v_add_f32_e32 v64, 0, v203
	v_exp_f32_e32 v68, v68
	v_fma_f32 v69, v69, s63, -v202
	v_fma_f32 v48, v48, s63, -v202
	v_add_f32_e32 v64, v65, v64
	v_exp_f32_e32 v69, v69
	v_fma_f32 v70, v70, s63, -v202
	v_exp_f32_e32 v205, v48
	v_fma_f32 v48, v49, s63, -v202
	v_add_f32_e32 v64, v66, v64
	v_exp_f32_e32 v70, v70
	v_fma_f32 v71, v71, s63, -v202
	v_exp_f32_e32 v206, v48
	v_fma_f32 v48, v50, s63, -v202
	v_add_f32_e32 v64, v67, v64
	v_exp_f32_e32 v71, v71
	v_fma_f32 v72, v72, s63, -v202
	v_exp_f32_e32 v207, v48
	v_fma_f32 v48, v51, s63, -v202
	v_add_f32_e32 v64, v68, v64
	v_exp_f32_e32 v72, v72
	v_fma_f32 v73, v73, s63, -v202
	v_exp_f32_e32 v208, v48
	v_fma_f32 v48, v52, s63, -v202
	v_add_f32_e32 v64, v69, v64
	v_exp_f32_e32 v73, v73
	v_fma_f32 v74, v74, s63, -v202
	v_exp_f32_e32 v209, v48
	v_fma_f32 v48, v53, s63, -v202
	v_add_f32_e32 v64, v70, v64
	v_exp_f32_e32 v74, v74
	v_fma_f32 v75, v75, s63, -v202
	v_exp_f32_e32 v210, v48
	v_fma_f32 v48, v54, s63, -v202
	v_add_f32_e32 v64, v71, v64
	v_exp_f32_e32 v75, v75
	v_fma_f32 v76, v76, s63, -v202
	v_exp_f32_e32 v211, v48
	v_fma_f32 v48, v55, s63, -v202
	v_add_f32_e32 v64, v72, v64
	v_exp_f32_e32 v76, v76
	v_fma_f32 v77, v77, s63, -v202
	v_exp_f32_e32 v212, v48
	v_fma_f32 v48, v56, s63, -v202
	v_add_f32_e32 v64, v73, v64
	v_exp_f32_e32 v77, v77
	v_fma_f32 v78, v78, s63, -v202
	v_exp_f32_e32 v213, v48
	v_fma_f32 v48, v57, s63, -v202
	v_add_f32_e32 v64, v74, v64
	v_exp_f32_e32 v78, v78
	v_fma_f32 v79, v79, s63, -v202
	v_exp_f32_e32 v214, v48
	v_fma_f32 v48, v58, s63, -v202
	v_add_f32_e32 v64, v75, v64
	v_exp_f32_e32 v79, v79
	v_exp_f32_e32 v215, v48
	v_fma_f32 v48, v59, s63, -v202
	v_add_f32_e32 v64, v76, v64
	v_exp_f32_e32 v216, v48
	v_fma_f32 v48, v60, s63, -v202
	v_add_f32_e32 v64, v77, v64
	v_exp_f32_e32 v217, v48
	v_fma_f32 v48, v61, s63, -v202
	v_sub_f32_e32 v201, v201, v202
	v_add_f32_e32 v64, v78, v64
	v_exp_f32_e32 v218, v48
	v_fma_f32 v48, v62, s63, -v202
	v_add_f32_e32 v204, v79, v64
	v_exp_f32_e32 v64, v201
	v_exp_f32_e32 v201, v48
	v_fma_f32 v48, v63, s63, -v202
	v_exp_f32_e32 v63, v48
	v_add_f32_e32 v48, v205, v204
	v_add_f32_e32 v48, v206, v48
	v_add_f32_e32 v48, v207, v48
	v_add_f32_e32 v48, v208, v48
	v_add_f32_e32 v48, v209, v48
	v_add_f32_e32 v48, v210, v48
	v_add_f32_e32 v48, v211, v48
	v_add_f32_e32 v48, v212, v48
	v_add_f32_e32 v48, v213, v48
	v_add_f32_e32 v48, v214, v48
	v_add_f32_e32 v48, v215, v48
	v_add_f32_e32 v48, v216, v48
	v_add_f32_e32 v48, v217, v48
	v_add_f32_e32 v48, v218, v48
	v_pk_mul_f32 v[46:47], v[46:47], v[64:65] op_sel_hi:[1,0]
	v_pk_mul_f32 v[44:45], v[44:45], v[64:65] op_sel_hi:[1,0]
	v_pk_mul_f32 v[42:43], v[42:43], v[64:65] op_sel_hi:[1,0]
	v_pk_mul_f32 v[40:41], v[40:41], v[64:65] op_sel_hi:[1,0]
	v_pk_mul_f32 v[38:39], v[38:39], v[64:65] op_sel_hi:[1,0]
	v_pk_mul_f32 v[36:37], v[36:37], v[64:65] op_sel_hi:[1,0]
	v_pk_mul_f32 v[34:35], v[34:35], v[64:65] op_sel_hi:[1,0]
	v_pk_mul_f32 v[32:33], v[32:33], v[64:65] op_sel_hi:[1,0]
	v_pk_mul_f32 v[30:31], v[30:31], v[64:65] op_sel_hi:[1,0]
	v_pk_mul_f32 v[28:29], v[28:29], v[64:65] op_sel_hi:[1,0]
	v_pk_mul_f32 v[26:27], v[26:27], v[64:65] op_sel_hi:[1,0]
	v_pk_mul_f32 v[24:25], v[24:25], v[64:65] op_sel_hi:[1,0]
	v_pk_mul_f32 v[22:23], v[22:23], v[64:65] op_sel_hi:[1,0]
	v_pk_mul_f32 v[20:21], v[20:21], v[64:65] op_sel_hi:[1,0]
	v_pk_mul_f32 v[18:19], v[18:19], v[64:65] op_sel_hi:[1,0]
	v_pk_mul_f32 v[16:17], v[16:17], v[64:65] op_sel_hi:[1,0]
	v_add_f32_e32 v48, v201, v48
	v_add_f32_e32 v202, v63, v48
	v_cvt_pk_bf16_f32 v48, v203, v65
	v_cvt_pk_bf16_f32 v49, v66, v67
	v_cvt_pk_bf16_f32 v50, v68, v69
	v_cvt_pk_bf16_f32 v51, v70, v71
	v_cvt_pk_bf16_f32 v52, v72, v73
	v_cvt_pk_bf16_f32 v53, v74, v75
	v_cvt_pk_bf16_f32 v54, v76, v77
	v_cvt_pk_bf16_f32 v55, v78, v79
	v_cvt_pk_bf16_f32 v56, v205, v206
	v_cvt_pk_bf16_f32 v57, v207, v208
	v_cvt_pk_bf16_f32 v58, v209, v210
	v_cvt_pk_bf16_f32 v59, v211, v212
	v_cvt_pk_bf16_f32 v60, v213, v214
	v_cvt_pk_bf16_f32 v61, v215, v216
	v_cvt_pk_bf16_f32 v62, v217, v218
	v_cvt_pk_bf16_f32 v63, v201, v63
	v_mfma_f32_32x32x16_bf16 v[32:47], v[140:143], v[48:51], v[32:47]
	v_fmac_f32_e32 v202, v200, v64
	v_mov_b32_e32 v201, v15
	v_mov_b32_e32 v200, v202
	v_mfma_f32_32x32x16_bf16 v[16:31], v[124:127], v[48:51], v[16:31]
	v_mfma_f32_32x32x16_bf16 v[32:47], v[136:139], v[52:55], v[32:47]
	v_mfma_f32_32x32x16_bf16 v[16:31], v[10:13], v[52:55], v[16:31]
	v_mfma_f32_32x32x16_bf16 v[32:47], v[132:135], v[56:59], v[32:47]
	v_mfma_f32_32x32x16_bf16 v[16:31], v[6:9], v[56:59], v[16:31]
	v_mfma_f32_32x32x16_bf16 v[32:47], v[128:131], v[60:63], v[32:47]
	v_mfma_f32_32x32x16_bf16 v[16:31], v[2:5], v[60:63], v[16:31]
	s_add_i32 s0, s19, 1
	s_cmp_gt_i32 s0, s69
	s_cbranch_scc0 .LBB0_624

.Lmla_fast_l0:
	s_mul_i32 s1, s18, 0xa800
	v_add3_u32 v14, s1, v148, v191
	v_add_u32_e32 v0, s1, v183
	v_add3_u32 v0, v0, v184, v185
	ds_read_b128 v[2:5], v14 offset:0
	ds_read_b128 v[6:9], v14 offset:32
	ds_read_b128 v[10:13], v14 offset:64
	ds_read_b128 v[140:143], v14 offset:96
	s_cmp_lg_u32 s98, 0
	s_cbranch_scc1 .Lmla_l0_negm_ok
	v_xor_b32_e32 v124, 0x80000000, v201
	v_xor_b32_e32 v125, 0x80000000, v201
	v_xor_b32_e32 v126, 0x80000000, v201
	v_xor_b32_e32 v127, 0x80000000, v201
	v_xor_b32_e32 v128, 0x80000000, v201
	v_xor_b32_e32 v129, 0x80000000, v201
	v_xor_b32_e32 v130, 0x80000000, v201
	v_xor_b32_e32 v131, 0x80000000, v201
	v_xor_b32_e32 v132, 0x80000000, v201
	v_xor_b32_e32 v133, 0x80000000, v201
	v_xor_b32_e32 v134, 0x80000000, v201
	v_xor_b32_e32 v135, 0x80000000, v201
	v_xor_b32_e32 v136, 0x80000000, v201
	v_xor_b32_e32 v137, 0x80000000, v201
	v_xor_b32_e32 v138, 0x80000000, v201
	v_xor_b32_e32 v139, 0x80000000, v201
	s_mov_b32 s98, 1
.Lmla_l0_negm_ok:
	s_nop 1
	s_waitcnt lgkmcnt(3)
	v_mfma_f32_32x32x16_bf16 v[64:79], v[2:5], v[92:95], v[124:139]
	ds_read_b128 v[234:237], v14 offset:128
	s_waitcnt lgkmcnt(3)
	v_mfma_f32_32x32x16_bf16 v[64:79], v[6:9], v[96:99], v[64:79]
	ds_read_b128 v[240:243], v14 offset:160
	s_waitcnt lgkmcnt(3)
	v_mfma_f32_32x32x16_bf16 v[64:79], v[10:13], v[100:103], v[64:79]
	ds_read_b128 v[2:5], v14 offset:6656
	s_waitcnt lgkmcnt(3)
	v_mfma_f32_32x32x16_bf16 v[64:79], v[140:143], v[104:107], v[64:79]
	ds_read_b128 v[6:9], v14 offset:6688
	s_waitcnt lgkmcnt(3)
	v_mfma_f32_32x32x16_bf16 v[64:79], v[234:237], v[116:119], v[64:79]
	ds_read_b128 v[10:13], v14 offset:6720
	s_waitcnt lgkmcnt(3)
	v_mfma_f32_32x32x16_bf16 v[64:79], v[240:243], v[120:123], v[64:79]
	ds_read_b128 v[140:143], v14 offset:6752
	s_waitcnt lgkmcnt(3)
	v_mfma_f32_32x32x16_bf16 v[48:63], v[2:5], v[92:95], v[124:139]
	ds_read_b128 v[234:237], v14 offset:6784
	s_waitcnt lgkmcnt(3)
	v_mfma_f32_32x32x16_bf16 v[48:63], v[6:9], v[96:99], v[48:63]
	ds_read_b128 v[240:243], v14 offset:6816
	s_waitcnt lgkmcnt(3)
	v_mfma_f32_32x32x16_bf16 v[48:63], v[10:13], v[100:103], v[48:63]
	ds_read_b128 v[2:5], v14 offset:21504
	s_waitcnt lgkmcnt(3)
	v_mfma_f32_32x32x16_bf16 v[48:63], v[140:143], v[104:107], v[48:63]
	ds_read_b128 v[6:9], v14 offset:21536
	s_waitcnt lgkmcnt(3)
	v_mfma_f32_32x32x16_bf16 v[48:63], v[234:237], v[116:119], v[48:63]
	ds_read_b128 v[10:13], v14 offset:21568
	s_waitcnt lgkmcnt(3)
	v_mfma_f32_32x32x16_bf16 v[48:63], v[240:243], v[120:123], v[48:63]
	ds_read_b128 v[140:143], v14 offset:21600
	v_exp_f32_e32 v64, v64
	v_exp_f32_e32 v65, v65
	s_waitcnt lgkmcnt(3)
	v_mfma_f32_32x32x16_bf16 v[202:217], v[2:5], v[92:95], v[124:139]
	ds_read_b128 v[234:237], v14 offset:21632
	v_exp_f32_e32 v66, v66
	v_exp_f32_e32 v67, v67
	v_exp_f32_e32 v68, v68
	v_exp_f32_e32 v69, v69
	v_exp_f32_e32 v70, v70
	s_waitcnt lgkmcnt(3)
	v_mfma_f32_32x32x16_bf16 v[202:217], v[6:9], v[96:99], v[202:217]
	ds_read_b128 v[240:243], v14 offset:21664
	v_exp_f32_e32 v71, v71
	v_pk_add_f32 v[246:247], v[64:65], v[66:67]
	v_exp_f32_e32 v72, v72
	v_exp_f32_e32 v73, v73
	v_exp_f32_e32 v74, v74
	s_waitcnt lgkmcnt(3)
	v_mfma_f32_32x32x16_bf16 v[202:217], v[10:13], v[100:103], v[202:217]
	ds_read_b128 v[2:5], v14 offset:28160
	v_exp_f32_e32 v75, v75
	v_pk_add_f32 v[248:249], v[68:69], v[70:71]
	v_exp_f32_e32 v76, v76
	v_exp_f32_e32 v77, v77
	v_pk_add_f32 v[246:247], v[246:247], v[72:73]
	s_waitcnt lgkmcnt(3)
	v_mfma_f32_32x32x16_bf16 v[202:217], v[140:143], v[104:107], v[202:217]
	ds_read_b128 v[6:9], v14 offset:28192
	v_exp_f32_e32 v78, v78
	v_exp_f32_e32 v79, v79
	v_pk_add_f32 v[248:249], v[248:249], v[74:75]
	v_exp_f32_e32 v48, v48
	v_exp_f32_e32 v49, v49
	s_waitcnt lgkmcnt(3)
	v_mfma_f32_32x32x16_bf16 v[202:217], v[234:237], v[116:119], v[202:217]
	ds_read_b128 v[10:13], v14 offset:28224
	v_pk_add_f32 v[246:247], v[246:247], v[76:77]
	v_exp_f32_e32 v50, v50
	v_exp_f32_e32 v51, v51
	v_pk_add_f32 v[248:249], v[248:249], v[78:79]
	v_exp_f32_e32 v52, v52
	s_waitcnt lgkmcnt(3)
	v_mfma_f32_32x32x16_bf16 v[202:217], v[240:243], v[120:123], v[202:217]
	ds_read_b128 v[140:143], v14 offset:28256
	v_exp_f32_e32 v53, v53
	v_pk_add_f32 v[246:247], v[246:247], v[48:49]
	v_exp_f32_e32 v54, v54
	v_exp_f32_e32 v55, v55
	v_pk_add_f32 v[248:249], v[248:249], v[50:51]
	s_waitcnt lgkmcnt(3)
	v_mfma_f32_32x32x16_bf16 v[218:233], v[2:5], v[92:95], v[124:139]
	ds_read_b128 v[234:237], v14 offset:28288
	v_exp_f32_e32 v56, v56
	v_exp_f32_e32 v57, v57
	v_pk_add_f32 v[246:247], v[246:247], v[52:53]
	v_exp_f32_e32 v58, v58
	v_exp_f32_e32 v59, v59
	s_waitcnt lgkmcnt(3)
	v_mfma_f32_32x32x16_bf16 v[218:233], v[6:9], v[96:99], v[218:233]
	ds_read_b128 v[240:243], v14 offset:28320
	v_pk_add_f32 v[248:249], v[248:249], v[54:55]
	v_exp_f32_e32 v60, v60
	v_exp_f32_e32 v61, v61
	v_pk_add_f32 v[246:247], v[246:247], v[56:57]
	v_exp_f32_e32 v62, v62
	s_waitcnt lgkmcnt(3)
	v_mfma_f32_32x32x16_bf16 v[218:233], v[10:13], v[100:103], v[218:233]
	ds_read_b64_tr_b16 v[2:3], v0 offset:13312
	ds_read_b64_tr_b16 v[4:5], v0 offset:13824
	v_exp_f32_e32 v63, v63
	v_pk_add_f32 v[248:249], v[248:249], v[58:59]
	v_pk_add_f32 v[246:247], v[246:247], v[60:61]
	v_pk_add_f32 v[248:249], v[248:249], v[62:63]
	v_pk_add_f32 v[246:247], v[246:247], v[248:249]
	s_waitcnt lgkmcnt(4)
	v_mfma_f32_32x32x16_bf16 v[218:233], v[140:143], v[104:107], v[218:233]
	ds_read_b64_tr_b16 v[6:7], v0 offset:17408
	ds_read_b64_tr_b16 v[8:9], v0 offset:17920
	v_add_f32_e32 v250, v246, v247
	v_cmp_ngt_f32_e32 vcc, 0x43800000, v250
	s_cbranch_vccnz .Lmla_l0_fbA
	v_add_f32_e32 v200, v200, v250
	v_cvt_pk_bf16_f32 v64, v64, v65
	v_cvt_pk_bf16_f32 v65, v66, v67
	s_waitcnt lgkmcnt(5)
	v_mfma_f32_32x32x16_bf16 v[218:233], v[234:237], v[116:119], v[218:233]
	ds_read_b64_tr_b16 v[10:11], v0 offset:14336
	ds_read_b64_tr_b16 v[12:13], v0 offset:14848
	v_cvt_pk_bf16_f32 v66, v68, v69
	v_cvt_pk_bf16_f32 v67, v70, v71
	v_cvt_pk_bf16_f32 v68, v72, v73
	v_cvt_pk_bf16_f32 v69, v74, v75
	v_cvt_pk_bf16_f32 v70, v76, v77
	s_waitcnt lgkmcnt(6)
	v_mfma_f32_32x32x16_bf16 v[218:233], v[240:243], v[120:123], v[218:233]
	ds_read_b64_tr_b16 v[140:141], v0 offset:18432
	ds_read_b64_tr_b16 v[142:143], v0 offset:18944
	v_cvt_pk_bf16_f32 v71, v78, v79
	v_cvt_pk_bf16_f32 v48, v48, v49
	v_cvt_pk_bf16_f32 v49, v50, v51
	v_cvt_pk_bf16_f32 v50, v52, v53
	v_cvt_pk_bf16_f32 v51, v54, v55
	v_cvt_pk_bf16_f32 v52, v56, v57
	v_cvt_pk_bf16_f32 v53, v58, v59
	v_cvt_pk_bf16_f32 v54, v60, v61
	v_cvt_pk_bf16_f32 v55, v62, v63
	v_exp_f32_e32 v202, v202
	v_exp_f32_e32 v203, v203
	s_waitcnt lgkmcnt(6)
	v_mfma_f32_32x32x16_bf16 v[32:47], v[2:5], v[64:67], v[32:47]
	ds_read_b64_tr_b16 v[234:235], v0 offset:15360
	ds_read_b64_tr_b16 v[236:237], v0 offset:15872
	v_exp_f32_e32 v204, v204
	v_exp_f32_e32 v205, v205
	v_exp_f32_e32 v206, v206
	v_exp_f32_e32 v207, v207
	v_exp_f32_e32 v208, v208
	s_waitcnt lgkmcnt(6)
	v_mfma_f32_32x32x16_bf16 v[16:31], v[6:9], v[64:67], v[16:31]
	ds_read_b64_tr_b16 v[240:241], v0 offset:19456
	ds_read_b64_tr_b16 v[242:243], v0 offset:19968
	v_exp_f32_e32 v209, v209
	v_pk_add_f32 v[246:247], v[202:203], v[204:205]
	v_exp_f32_e32 v210, v210
	v_exp_f32_e32 v211, v211
	v_exp_f32_e32 v212, v212
	s_waitcnt lgkmcnt(6)
	v_mfma_f32_32x32x16_bf16 v[32:47], v[10:13], v[68:71], v[32:47]
	ds_read_b64_tr_b16 v[2:3], v0 offset:16384
	ds_read_b64_tr_b16 v[4:5], v0 offset:16896
	v_exp_f32_e32 v213, v213
	v_pk_add_f32 v[248:249], v[206:207], v[208:209]
	v_exp_f32_e32 v214, v214
	v_exp_f32_e32 v215, v215
	v_pk_add_f32 v[246:247], v[246:247], v[210:211]
	s_waitcnt lgkmcnt(6)
	v_mfma_f32_32x32x16_bf16 v[16:31], v[140:143], v[68:71], v[16:31]
	ds_read_b64_tr_b16 v[6:7], v0 offset:20480
	ds_read_b64_tr_b16 v[8:9], v0 offset:20992
	v_exp_f32_e32 v216, v216
	v_exp_f32_e32 v217, v217
	v_pk_add_f32 v[248:249], v[248:249], v[212:213]
	v_exp_f32_e32 v218, v218
	v_exp_f32_e32 v219, v219
	s_waitcnt lgkmcnt(6)
	v_mfma_f32_32x32x16_bf16 v[32:47], v[234:237], v[48:51], v[32:47]
	ds_read_b64_tr_b16 v[10:11], v0 offset:34816
	ds_read_b64_tr_b16 v[12:13], v0 offset:35328
	v_pk_add_f32 v[246:247], v[246:247], v[214:215]
	v_exp_f32_e32 v220, v220
	v_exp_f32_e32 v221, v221
	v_pk_add_f32 v[248:249], v[248:249], v[216:217]
	v_exp_f32_e32 v222, v222
	s_waitcnt lgkmcnt(6)
	v_mfma_f32_32x32x16_bf16 v[16:31], v[240:243], v[48:51], v[16:31]
	ds_read_b64_tr_b16 v[140:141], v0 offset:38912
	ds_read_b64_tr_b16 v[142:143], v0 offset:39424
	v_exp_f32_e32 v223, v223
	v_pk_add_f32 v[246:247], v[246:247], v[218:219]
	v_exp_f32_e32 v224, v224
	v_exp_f32_e32 v225, v225
	v_pk_add_f32 v[248:249], v[248:249], v[220:221]
	s_waitcnt lgkmcnt(6)
	v_mfma_f32_32x32x16_bf16 v[32:47], v[2:5], v[52:55], v[32:47]
	ds_read_b64_tr_b16 v[234:235], v0 offset:35840
	ds_read_b64_tr_b16 v[236:237], v0 offset:36352
	v_exp_f32_e32 v226, v226
	v_exp_f32_e32 v227, v227
	v_pk_add_f32 v[246:247], v[246:247], v[222:223]
	v_exp_f32_e32 v228, v228
	v_exp_f32_e32 v229, v229
	s_waitcnt lgkmcnt(6)
	v_mfma_f32_32x32x16_bf16 v[16:31], v[6:9], v[52:55], v[16:31]
	ds_read_b64_tr_b16 v[240:241], v0 offset:39936
	ds_read_b64_tr_b16 v[242:243], v0 offset:40448
	v_pk_add_f32 v[248:249], v[248:249], v[224:225]
	v_exp_f32_e32 v230, v230
	v_exp_f32_e32 v231, v231
	v_pk_add_f32 v[246:247], v[246:247], v[226:227]
	v_exp_f32_e32 v232, v232
	v_exp_f32_e32 v233, v233
	v_pk_add_f32 v[248:249], v[248:249], v[228:229]
	v_pk_add_f32 v[246:247], v[246:247], v[230:231]
	v_pk_add_f32 v[248:249], v[248:249], v[232:233]
	v_pk_add_f32 v[246:247], v[246:247], v[248:249]
	v_add_f32_e32 v250, v246, v247
	v_cmp_ngt_f32_e32 vcc, 0x43800000, v250
	s_cbranch_vccnz .Lmla_l0_fbB
	v_add_f32_e32 v200, v200, v250
	v_cvt_pk_bf16_f32 v202, v202, v203
	v_cvt_pk_bf16_f32 v203, v204, v205
	v_cvt_pk_bf16_f32 v204, v206, v207
	v_cvt_pk_bf16_f32 v205, v208, v209
	v_cvt_pk_bf16_f32 v206, v210, v211
	v_cvt_pk_bf16_f32 v207, v212, v213
	v_cvt_pk_bf16_f32 v208, v214, v215
	v_cvt_pk_bf16_f32 v209, v216, v217
	v_cvt_pk_bf16_f32 v218, v218, v219
	v_cvt_pk_bf16_f32 v219, v220, v221
	v_cvt_pk_bf16_f32 v220, v222, v223
	v_cvt_pk_bf16_f32 v221, v224, v225
	v_cvt_pk_bf16_f32 v222, v226, v227
	v_cvt_pk_bf16_f32 v223, v228, v229
	v_cvt_pk_bf16_f32 v224, v230, v231
	v_cvt_pk_bf16_f32 v225, v232, v233
	s_waitcnt lgkmcnt(6)
	v_mfma_f32_32x32x16_bf16 v[32:47], v[10:13], v[202:205], v[32:47]
	ds_read_b64_tr_b16 v[2:3], v0 offset:36864
	ds_read_b64_tr_b16 v[4:5], v0 offset:37376
	s_waitcnt lgkmcnt(6)
	v_mfma_f32_32x32x16_bf16 v[16:31], v[140:143], v[202:205], v[16:31]
	ds_read_b64_tr_b16 v[6:7], v0 offset:40960
	ds_read_b64_tr_b16 v[8:9], v0 offset:41472
	s_waitcnt lgkmcnt(6)
	v_mfma_f32_32x32x16_bf16 v[32:47], v[234:237], v[206:209], v[32:47]
	ds_read_b64_tr_b16 v[10:11], v0 offset:37888
	ds_read_b64_tr_b16 v[12:13], v0 offset:38400
	s_waitcnt lgkmcnt(6)
	v_mfma_f32_32x32x16_bf16 v[16:31], v[240:243], v[206:209], v[16:31]
	ds_read_b64_tr_b16 v[140:141], v0 offset:41984
	ds_read_b64_tr_b16 v[142:143], v0 offset:42496
	s_waitcnt lgkmcnt(6)
	v_mfma_f32_32x32x16_bf16 v[32:47], v[2:5], v[218:221], v[32:47]
	s_waitcnt lgkmcnt(4)
	v_mfma_f32_32x32x16_bf16 v[16:31], v[6:9], v[218:221], v[16:31]
	s_waitcnt lgkmcnt(2)
	v_mfma_f32_32x32x16_bf16 v[32:47], v[10:13], v[222:225], v[32:47]
	s_waitcnt lgkmcnt(0)
	v_mfma_f32_32x32x16_bf16 v[16:31], v[140:143], v[222:225], v[16:31]
	s_branch .LBB0_622
.Lmla_l0_fbA:
	s_waitcnt lgkmcnt(0)
	s_mov_b32 s98, 0
	s_branch .Lmla_orig0_l0

.LBB0_628:
	v_and_b32_e32 v15, 64, v163
	v_xor_b32_e32 v14, 32, v163
	v_add_u32_e32 v15, 64, v15
	v_cmp_lt_i32_e32 vcc, v14, v15
	v_max_f32_e32 v15, v201, v201
	s_nop 0
	v_cndmask_b32_e32 v14, v163, v14, vcc
	v_lshlrev_b32_e32 v14, 2, v14
	ds_bpermute_b32 v14, v14, v0
	v_max_f32_e32 v0, v0, v0
	s_waitcnt lgkmcnt(0)
	v_max_f32_e32 v14, v14, v14
	v_max_f32_e32 v0, v0, v14
	v_mul_f32_e32 v0, 1.0, v0
	v_max_f32_e32 v14, v15, v0
	v_cmp_neq_f32_e32 vcc, s62, v14
	s_nop 1
	v_cndmask_b32_e32 v15, 0, v14, vcc
	v_fma_f32 v64, v64, s63, -v15
	v_exp_f32_e32 v64, v64
	v_fma_f32 v65, v65, s63, -v15
	v_exp_f32_e32 v65, v65
	v_fma_f32 v66, v66, s63, -v15
	v_exp_f32_e32 v66, v66
	v_fma_f32 v67, v67, s63, -v15
	v_exp_f32_e32 v67, v67
	v_fma_f32 v68, v68, s63, -v15
	v_sub_f32_e32 v0, v201, v15
	v_add_f32_e32 v201, 0, v64
	v_exp_f32_e32 v68, v68
	v_fma_f32 v69, v69, s63, -v15
	v_add_f32_e32 v201, v65, v201
	v_exp_f32_e32 v69, v69
	v_fma_f32 v70, v70, s63, -v15
	v_fma_f32 v48, v48, s63, -v15
	v_add_f32_e32 v201, v66, v201
	v_exp_f32_e32 v70, v70
	v_fma_f32 v71, v71, s63, -v15
	v_exp_f32_e32 v202, v48
	v_fma_f32 v48, v49, s63, -v15
	v_add_f32_e32 v201, v67, v201
	v_exp_f32_e32 v71, v71
	v_fma_f32 v72, v72, s63, -v15
	v_exp_f32_e32 v203, v48
	v_fma_f32 v48, v50, s63, -v15
	v_add_f32_e32 v201, v68, v201
	v_exp_f32_e32 v72, v72
	v_fma_f32 v73, v73, s63, -v15
	v_exp_f32_e32 v204, v48
	v_fma_f32 v48, v51, s63, -v15
	v_add_f32_e32 v201, v69, v201
	v_exp_f32_e32 v73, v73
	v_fma_f32 v74, v74, s63, -v15
	v_exp_f32_e32 v205, v48
	v_fma_f32 v48, v52, s63, -v15
	v_add_f32_e32 v201, v70, v201
	v_exp_f32_e32 v74, v74
	v_fma_f32 v75, v75, s63, -v15
	v_exp_f32_e32 v206, v48
	v_fma_f32 v48, v53, s63, -v15
	v_add_f32_e32 v201, v71, v201
	v_exp_f32_e32 v75, v75
	v_fma_f32 v76, v76, s63, -v15
	v_exp_f32_e32 v207, v48
	v_fma_f32 v48, v54, s63, -v15
	v_add_f32_e32 v201, v72, v201
	v_exp_f32_e32 v76, v76
	v_fma_f32 v77, v77, s63, -v15
	v_exp_f32_e32 v208, v48
	v_fma_f32 v48, v55, s63, -v15
	v_add_f32_e32 v201, v73, v201
	v_exp_f32_e32 v77, v77
	v_fma_f32 v78, v78, s63, -v15
	v_exp_f32_e32 v209, v48
	v_fma_f32 v48, v56, s63, -v15
	v_add_f32_e32 v201, v74, v201
	v_exp_f32_e32 v78, v78
	v_fma_f32 v79, v79, s63, -v15
	v_exp_f32_e32 v210, v48
	v_fma_f32 v48, v57, s63, -v15
	v_add_f32_e32 v201, v75, v201
	v_exp_f32_e32 v79, v79
	v_exp_f32_e32 v211, v48
	v_fma_f32 v48, v58, s63, -v15
	v_add_f32_e32 v201, v76, v201
	v_exp_f32_e32 v212, v48
	v_fma_f32 v48, v59, s63, -v15
	v_add_f32_e32 v201, v77, v201
	v_exp_f32_e32 v213, v48
	v_fma_f32 v48, v60, s63, -v15
	v_add_f32_e32 v201, v78, v201
	v_exp_f32_e32 v214, v48
	v_fma_f32 v48, v61, s63, -v15
	v_add_f32_e32 v201, v79, v201
	v_exp_f32_e32 v215, v48
	v_fma_f32 v48, v62, s63, -v15
	v_exp_f32_e32 v216, v48
	v_add_f32_e32 v48, v202, v201
	v_add_f32_e32 v48, v203, v48
	v_add_f32_e32 v48, v204, v48
	v_add_f32_e32 v48, v205, v48
	v_add_f32_e32 v48, v206, v48
	v_add_f32_e32 v48, v207, v48
	v_add_f32_e32 v48, v208, v48
	v_add_f32_e32 v48, v209, v48
	v_add_f32_e32 v48, v210, v48
	v_add_f32_e32 v48, v211, v48
	v_exp_f32_e32 v0, v0
	v_fma_f32 v15, v63, s63, -v15
	v_add_f32_e32 v48, v212, v48
	v_exp_f32_e32 v15, v15
	v_add_f32_e32 v48, v213, v48
	v_add_f32_e32 v48, v214, v48
	v_add_f32_e32 v48, v215, v48
	v_pk_mul_f32 v[46:47], v[46:47], v[0:1] op_sel_hi:[1,0]
	v_pk_mul_f32 v[44:45], v[44:45], v[0:1] op_sel_hi:[1,0]
	v_pk_mul_f32 v[42:43], v[42:43], v[0:1] op_sel_hi:[1,0]
	v_pk_mul_f32 v[40:41], v[40:41], v[0:1] op_sel_hi:[1,0]
	v_pk_mul_f32 v[38:39], v[38:39], v[0:1] op_sel_hi:[1,0]
	v_pk_mul_f32 v[36:37], v[36:37], v[0:1] op_sel_hi:[1,0]
	v_pk_mul_f32 v[34:35], v[34:35], v[0:1] op_sel_hi:[1,0]
	v_pk_mul_f32 v[32:33], v[32:33], v[0:1] op_sel_hi:[1,0]
	v_pk_mul_f32 v[30:31], v[30:31], v[0:1] op_sel_hi:[1,0]
	v_pk_mul_f32 v[28:29], v[28:29], v[0:1] op_sel_hi:[1,0]
	v_pk_mul_f32 v[26:27], v[26:27], v[0:1] op_sel_hi:[1,0]
	v_pk_mul_f32 v[24:25], v[24:25], v[0:1] op_sel_hi:[1,0]
	v_pk_mul_f32 v[22:23], v[22:23], v[0:1] op_sel_hi:[1,0]
	v_pk_mul_f32 v[20:21], v[20:21], v[0:1] op_sel_hi:[1,0]
	v_pk_mul_f32 v[18:19], v[18:19], v[0:1] op_sel_hi:[1,0]
	v_pk_mul_f32 v[16:17], v[16:17], v[0:1] op_sel_hi:[1,0]
	v_add_f32_e32 v48, v216, v48
	v_add_f32_e32 v217, v15, v48
	v_cvt_pk_bf16_f32 v48, v64, v65
	v_cvt_pk_bf16_f32 v49, v66, v67
	v_cvt_pk_bf16_f32 v50, v68, v69
	v_cvt_pk_bf16_f32 v51, v70, v71
	v_cvt_pk_bf16_f32 v52, v72, v73
	v_cvt_pk_bf16_f32 v53, v74, v75
	v_cvt_pk_bf16_f32 v54, v76, v77
	v_cvt_pk_bf16_f32 v55, v78, v79
	v_cvt_pk_bf16_f32 v56, v202, v203
	v_cvt_pk_bf16_f32 v57, v204, v205
	v_cvt_pk_bf16_f32 v58, v206, v207
	v_cvt_pk_bf16_f32 v59, v208, v209
	v_cvt_pk_bf16_f32 v60, v210, v211
	v_cvt_pk_bf16_f32 v61, v212, v213
	v_cvt_pk_bf16_f32 v62, v214, v215
	v_cvt_pk_bf16_f32 v63, v216, v15
	v_mfma_f32_32x32x16_bf16 v[32:47], v[140:143], v[48:51], v[32:47]
	v_fmac_f32_e32 v217, v200, v0
	v_mov_b32_e32 v201, v14
	v_mov_b32_e32 v200, v217
	v_mfma_f32_32x32x16_bf16 v[16:31], v[124:127], v[48:51], v[16:31]
	v_mfma_f32_32x32x16_bf16 v[32:47], v[136:139], v[52:55], v[32:47]
	v_mfma_f32_32x32x16_bf16 v[16:31], v[10:13], v[52:55], v[16:31]
	v_mfma_f32_32x32x16_bf16 v[32:47], v[132:135], v[56:59], v[32:47]
	v_mfma_f32_32x32x16_bf16 v[16:31], v[6:9], v[56:59], v[16:31]
	v_mfma_f32_32x32x16_bf16 v[32:47], v[128:131], v[60:63], v[32:47]
	v_mfma_f32_32x32x16_bf16 v[16:31], v[2:5], v[60:63], v[16:31]
	s_xor_b32 s18, s18, 1
	s_and_b64 vcc, exec, s[14:15]
	s_cbranch_vccz .LBB0_593

.LBB0_1307:
	s_lshl_b32 s9, s6, 1
	s_lshl_b32 s15, s7, 1
	v_or_b32_e32 v2, s9, v1
	v_or_b32_e32 v90, s15, v0
	s_add_i32 s16, s9, 4
	s_add_i32 s17, s15, 4
	s_add_i32 s18, s9, 8
	s_add_i32 s19, s15, 8
	s_add_i32 s20, s9, 12
	s_add_i32 s23, s15, 12
	s_add_i32 s35, s9, 16
	s_add_i32 s38, s15, 16
	s_add_i32 s39, s9, 20
	s_add_i32 s42, s15, 20
	s_add_i32 s43, s9, 24
	s_add_i32 s44, s15, 24
	s_add_i32 s9, s9, 28
	s_add_i32 s15, s15, 28
	v_add_u32_e32 v56, s1, v90
	v_or_b32_e32 v91, s16, v1
	v_or_b32_e32 v92, s17, v0
	v_or_b32_e32 v93, s18, v1
	v_or_b32_e32 v94, s19, v0
	v_or_b32_e32 v95, s20, v1
	v_or_b32_e32 v96, s23, v0
	v_or_b32_e32 v97, s35, v1
	v_or_b32_e32 v98, s38, v0
	v_or_b32_e32 v99, s39, v1
	v_or_b32_e32 v100, s42, v0
	v_or_b32_e32 v101, s43, v1
	v_or_b32_e32 v102, s44, v0
	v_or_b32_e32 v103, s9, v1
	v_or_b32_e32 v104, s15, v0
	v_add_u32_e32 v58, s4, v2
	v_mad_u64_u32 v[56:57], s[16:17], v56, s11, v[50:51]
	v_add_u32_e32 v62, s4, v91
	v_add_u32_e32 v60, s1, v92
	v_add_u32_e32 v66, s4, v93
	v_add_u32_e32 v64, s1, v94
	v_add_u32_e32 v70, s4, v95
	v_add_u32_e32 v68, s1, v96
	v_add_u32_e32 v74, s4, v97
	v_add_u32_e32 v72, s1, v98
	v_add_u32_e32 v78, s4, v99
	v_add_u32_e32 v76, s1, v100
	v_add_u32_e32 v82, s4, v101
	v_add_u32_e32 v80, s1, v102
	v_add_u32_e32 v86, s4, v103
	v_add_u32_e32 v84, s1, v104
	v_mad_u64_u32 v[58:59], s[16:17], v58, s11, v[50:51]
	v_mad_u64_u32 v[60:61], s[16:17], v60, s11, v[50:51]
	v_mad_u64_u32 v[62:63], s[16:17], v62, s11, v[50:51]
	v_mad_u64_u32 v[64:65], s[16:17], v64, s11, v[50:51]
	v_mad_u64_u32 v[66:67], s[16:17], v66, s11, v[50:51]
	v_mad_u64_u32 v[68:69], s[16:17], v68, s11, v[50:51]
	v_mad_u64_u32 v[70:71], s[16:17], v70, s11, v[50:51]
	v_mad_u64_u32 v[72:73], s[16:17], v72, s11, v[50:51]
	v_mad_u64_u32 v[74:75], s[16:17], v74, s11, v[50:51]
	v_mad_u64_u32 v[76:77], s[16:17], v76, s11, v[50:51]
	v_mad_u64_u32 v[78:79], s[16:17], v78, s11, v[50:51]
	v_mad_u64_u32 v[80:81], s[16:17], v80, s11, v[50:51]
	v_mad_u64_u32 v[82:83], s[16:17], v82, s11, v[50:51]
	v_mad_u64_u32 v[84:85], s[16:17], v84, s11, v[50:51]
	v_mad_u64_u32 v[86:87], s[16:17], v86, s11, v[50:51]
	global_load_dword v105, v[56:57], off
	global_load_dword v106, v[58:59], off
	global_load_dword v107, v[60:61], off
	global_load_dword v108, v[62:63], off
	global_load_dword v109, v[64:65], off
	global_load_dword v110, v[66:67], off
	global_load_dword v111, v[68:69], off
	global_load_dword v112, v[70:71], off
	global_load_dword v113, v[72:73], off
	global_load_dword v114, v[74:75], off
	global_load_dword v115, v[76:77], off
	global_load_dword v116, v[78:79], off
	global_load_dword v117, v[80:81], off
	global_load_dword v118, v[82:83], off
	global_load_dword v119, v[84:85], off
	global_load_dword v120, v[86:87], off
	s_add_i32 s7, s7, 16
	s_add_i32 s6, s6, 16
	s_add_i32 s8, s8, -16
	v_mad_u64_u32 v[56:57], s[16:17], v90, s3, v[6:7]
	s_cmp_lg_u32 s8, 0
	v_mad_u64_u32 v[58:59], s[16:17], v2, s3, v[6:7]
	v_mad_u64_u32 v[60:61], s[16:17], v92, s3, v[6:7]
	v_mad_u64_u32 v[62:63], s[16:17], v91, s3, v[6:7]
	v_mad_u64_u32 v[64:65], s[16:17], v94, s3, v[6:7]
	v_mad_u64_u32 v[66:67], s[16:17], v93, s3, v[6:7]
	v_mad_u64_u32 v[68:69], s[16:17], v96, s3, v[6:7]
	v_mad_u64_u32 v[70:71], s[16:17], v95, s3, v[6:7]
	v_mad_u64_u32 v[72:73], s[16:17], v98, s3, v[6:7]
	v_mad_u64_u32 v[74:75], s[16:17], v97, s3, v[6:7]
	v_mad_u64_u32 v[76:77], s[16:17], v100, s3, v[6:7]
	v_mad_u64_u32 v[78:79], s[16:17], v99, s3, v[6:7]
	v_mad_u64_u32 v[80:81], s[16:17], v102, s3, v[6:7]
	v_mad_u64_u32 v[82:83], s[16:17], v101, s3, v[6:7]
	v_mad_u64_u32 v[84:85], s[16:17], v104, s3, v[6:7]
	v_mad_u64_u32 v[86:87], s[16:17], v103, s3, v[6:7]
	s_waitcnt vmcnt(15)
	ds_write_b32 v56, v105
	s_waitcnt vmcnt(14)
	ds_write_b32 v58, v106
	s_waitcnt vmcnt(13)
	ds_write_b32 v60, v107
	s_waitcnt vmcnt(12)
	ds_write_b32 v62, v108
	s_waitcnt vmcnt(11)
	ds_write_b32 v64, v109
	s_waitcnt vmcnt(10)
	ds_write_b32 v66, v110
	s_waitcnt vmcnt(9)
	ds_write_b32 v68, v111
	s_waitcnt vmcnt(8)
	ds_write_b32 v70, v112
	s_waitcnt vmcnt(7)
	ds_write_b32 v72, v113
	s_waitcnt vmcnt(6)
	ds_write_b32 v74, v114
	s_waitcnt vmcnt(5)
	ds_write_b32 v76, v115
	s_waitcnt vmcnt(4)
	ds_write_b32 v78, v116
	s_waitcnt vmcnt(3)
	ds_write_b32 v80, v117
	s_waitcnt vmcnt(2)
	ds_write_b32 v82, v118
	s_waitcnt vmcnt(1)
	ds_write_b32 v84, v119
	s_waitcnt vmcnt(0)
	ds_write_b32 v86, v120
	s_cbranch_scc1 .LBB0_1307
	s_waitcnt lgkmcnt(0)
	ds_read2_b32 v[50:51], v52 offset0:33 offset1:41
	ds_read2_b32 v[60:61], v52 offset1:8
	ds_read2_b32 v[62:63], v52 offset0:66 offset1:74
	ds_read2_b32 v[64:65], v52 offset0:99 offset1:107
	ds_read2_b32 v[66:67], v52 offset0:132 offset1:140
	ds_read2_b32 v[68:69], v52 offset0:165 offset1:173
	ds_read2_b32 v[70:71], v52 offset0:198 offset1:206
	ds_read2_b32 v[72:73], v52 offset0:231 offset1:239
	v_or_b32_e32 v2, s0, v7
	s_lshl_b32 s4, s1, 1
	v_mul_u32_u24_e32 v2, 0x180, v2
	v_lshl_add_u64 v[74:75], v[26:27], 0, s[4:5]
	v_lshlrev_b32_e32 v2, 1, v2
	v_lshl_add_u64 v[76:77], v[74:75], 0, v[2:3]
	v_or_b32_e32 v2, s0, v53
	s_waitcnt lgkmcnt(6)
	v_mul_f32_e32 v60, 0x3e16c740, v60
	v_mul_f32_e32 v50, 0x3e16c740, v50
	v_cvt_pk_bf16_f32 v56, v60, v50
	s_waitcnt lgkmcnt(4)
	v_mul_f32_e32 v62, 0x3e16c740, v62
	v_mul_f32_e32 v64, 0x3e16c740, v64
	v_cvt_pk_bf16_f32 v57, v62, v64
	s_waitcnt lgkmcnt(2)
	v_mul_f32_e32 v66, 0x3e16c740, v66
	v_mul_f32_e32 v68, 0x3e16c740, v68
	v_cvt_pk_bf16_f32 v58, v66, v68
	s_waitcnt lgkmcnt(0)
	v_mul_f32_e32 v70, 0x3e16c740, v70
	v_mul_f32_e32 v72, 0x3e16c740, v72
	v_cvt_pk_bf16_f32 v59, v70, v72
	v_mul_u32_u24_e32 v2, 0x180, v2
	global_store_dwordx4 v[76:77], v[56:59], off
	v_lshlrev_b32_e32 v2, 1, v2
	s_nop 0
	v_mul_f32_e32 v61, 0x3e16c740, v61
	v_mul_f32_e32 v51, 0x3e16c740, v51
	v_cvt_pk_bf16_f32 v56, v61, v51
	v_mul_f32_e32 v63, 0x3e16c740, v63
	v_mul_f32_e32 v65, 0x3e16c740, v65
	v_cvt_pk_bf16_f32 v57, v63, v65
	v_mul_f32_e32 v67, 0x3e16c740, v67
	v_mul_f32_e32 v69, 0x3e16c740, v69
	v_cvt_pk_bf16_f32 v58, v67, v69
	v_mul_f32_e32 v71, 0x3e16c740, v71
	v_mul_f32_e32 v73, 0x3e16c740, v73
	v_cvt_pk_bf16_f32 v59, v71, v73
	v_lshl_add_u64 v[50:51], v[74:75], 0, v[2:3]
	ds_read2_b32 v[60:61], v52 offset0:16 offset1:24
	ds_read2_b32 v[62:63], v52 offset0:49 offset1:57
	ds_read2_b32 v[64:65], v52 offset0:82 offset1:90
	ds_read2_b32 v[66:67], v52 offset0:115 offset1:123
	ds_read2_b32 v[68:69], v52 offset0:148 offset1:156
	ds_read2_b32 v[70:71], v52 offset0:181 offset1:189
	ds_read2_b32 v[72:73], v52 offset0:214 offset1:222
	ds_read2_b32 v[76:77], v52 offset0:247 offset1:255
	v_or_b32_e32 v2, s0, v54
	v_mul_u32_u24_e32 v2, 0x180, v2
	v_lshlrev_b32_e32 v2, 1, v2
	global_store_dwordx4 v[50:51], v[56:59], off
	v_lshl_add_u64 v[50:51], v[74:75], 0, v[2:3]
	v_or_b32_e32 v2, s0, v55
	v_mul_u32_u24_e32 v2, 0x180, v2
	s_waitcnt lgkmcnt(6)
	v_mul_f32_e32 v60, 0x3e16c740, v60
	v_mul_f32_e32 v62, 0x3e16c740, v62
	v_cvt_pk_bf16_f32 v56, v60, v62
	s_waitcnt lgkmcnt(4)
	v_mul_f32_e32 v64, 0x3e16c740, v64
	v_mul_f32_e32 v66, 0x3e16c740, v66
	v_cvt_pk_bf16_f32 v57, v64, v66
	s_waitcnt lgkmcnt(2)
	v_mul_f32_e32 v68, 0x3e16c740, v68
	v_mul_f32_e32 v70, 0x3e16c740, v70
	v_cvt_pk_bf16_f32 v58, v68, v70
	s_waitcnt lgkmcnt(0)
	v_mul_f32_e32 v72, 0x3e16c740, v72
	v_mul_f32_e32 v76, 0x3e16c740, v76
	v_cvt_pk_bf16_f32 v59, v72, v76
	v_lshlrev_b32_e32 v2, 1, v2
	global_store_dwordx4 v[50:51], v[56:59], off
	v_lshl_add_u64 v[50:51], v[74:75], 0, v[2:3]
	s_nop 0
	v_mul_f32_e32 v61, 0x3e16c740, v61
	v_mul_f32_e32 v63, 0x3e16c740, v63
	v_cvt_pk_bf16_f32 v56, v61, v63
	v_mul_f32_e32 v65, 0x3e16c740, v65
	v_mul_f32_e32 v67, 0x3e16c740, v67
	v_cvt_pk_bf16_f32 v57, v65, v67
	v_mul_f32_e32 v69, 0x3e16c740, v69
	v_mul_f32_e32 v71, 0x3e16c740, v71
	v_cvt_pk_bf16_f32 v58, v69, v71
	v_mul_f32_e32 v73, 0x3e16c740, v73
	v_mul_f32_e32 v77, 0x3e16c740, v77
	v_cvt_pk_bf16_f32 v59, v73, v77
	global_store_dwordx4 v[50:51], v[56:59], off
	s_waitcnt lgkmcnt(0)

.LBB0_1836:
	s_or_b64 exec, exec, s[2:3]
	s_mov_b32 s23, s95
	s_waitcnt lgkmcnt(0)
	s_barrier
	s_cmpk_gt_i32 s23, 0x1ff
	s_cbranch_scc1 .LBB0_1939
	s_cmpk_eq_i32 s72, 0x100
	s_cselect_b64 s[44:45], -1, 0
	s_lshl_b32 s0, s23, 2
	s_and_b32 s0, s0, 28
	s_ashr_i32 s1, s23, 7
	s_add_i32 s0, s0, s1
	s_bfe_u32 s1, s23, 0x40003
	s_lshl_b32 s0, s0, 4
	s_or_b32 s64, s0, s1
	s_add_u32 s65, s26, 0x17030000
	s_addc_u32 s66, s27, 0
	s_mov_b32 s67, 0
	v_mov_b32_e32 v1, 0
	v_mov_b32_e32 v160, 0xfffffb00
	s_movk_i32 s69, 0x2ff
	s_mov_b32 s74, 0x2aaaaaab
	s_movk_i32 s75, 0x600
	s_movk_i32 s76, 0xd0
	s_mov_b32 s77, 0xff800000
	s_mov_b32 s78, 1.0
	v_mov_b32_e32 v161, 0x5400
	v_mov_b32_e32 v162, 0xff800000
	v_mbcnt_hi_u32_b32 v163, -1, v239
	s_mov_b32 s79, s23
	s_branch .LBB0_1839

.LBB0_1906:
	s_cmp_lt_i32 s19, 0x80
	s_cbranch_scc1 .Lmla_nofast_l1
	s_add_i32 s0, s19, 64
	s_cmp_le_i32 s0, s84
	s_cbranch_scc1 .Lmla_fast_l1
.Lmla_nofast_l1:
	s_mov_b32 s98, 0
	s_mul_i32 s1, s18, 0xa800
	s_add_i32 s1, s1, 0
	s_sub_i32 s0, s19, 63
	v_add_u32_e32 v0, s1, v183
	s_cmp_le_i32 s0, s85
	v_add3_u32 v14, s1, v148, v191
	v_add3_u32 v0, v0, v184, v185
	s_cbranch_scc0 .LBB0_1913
.Lmla_orig0_l1:
	ds_read_b128 v[2:5], v14
	ds_read_b128 v[6:9], v14 offset:32
	ds_read_b128 v[10:13], v14 offset:64
	ds_read_b128 v[48:51], v14 offset:96
	ds_read_b128 v[52:55], v14 offset:128
	ds_read_b128 v[56:59], v14 offset:160
	ds_read_b128 v[60:63], v14 offset:6656
	ds_read_b128 v[124:127], v14 offset:6688
	ds_read_b128 v[128:131], v14 offset:6720
	ds_read_b128 v[132:135], v14 offset:6752
	ds_read_b128 v[136:139], v14 offset:6784
	ds_read_b128 v[140:143], v14 offset:6816
	s_waitcnt lgkmcnt(11)
	v_mfma_f32_32x32x16_bf16 v[64:79], v[2:5], v[92:95], 0
	s_waitcnt lgkmcnt(10)
	v_mfma_f32_32x32x16_bf16 v[64:79], v[6:9], v[96:99], v[64:79]
	s_waitcnt lgkmcnt(9)
	v_mfma_f32_32x32x16_bf16 v[64:79], v[10:13], v[100:103], v[64:79]
	s_waitcnt lgkmcnt(8)
	v_mfma_f32_32x32x16_bf16 v[64:79], v[48:51], v[104:107], v[64:79]
	s_waitcnt lgkmcnt(7)
	v_mfma_f32_32x32x16_bf16 v[64:79], v[52:55], v[116:119], v[64:79]
	s_waitcnt lgkmcnt(6)
	v_mfma_f32_32x32x16_bf16 v[64:79], v[56:59], v[120:123], v[64:79]
	s_waitcnt lgkmcnt(5)
	v_mfma_f32_32x32x16_bf16 v[48:63], v[60:63], v[92:95], 0
	s_waitcnt lgkmcnt(4)
	v_mfma_f32_32x32x16_bf16 v[48:63], v[124:127], v[96:99], v[48:63]
	s_waitcnt lgkmcnt(3)
	v_mfma_f32_32x32x16_bf16 v[48:63], v[128:131], v[100:103], v[48:63]
	s_waitcnt lgkmcnt(2)
	v_mfma_f32_32x32x16_bf16 v[48:63], v[132:135], v[104:107], v[48:63]
	s_waitcnt lgkmcnt(1)
	v_mfma_f32_32x32x16_bf16 v[48:63], v[136:139], v[116:119], v[48:63]
	s_waitcnt lgkmcnt(0)
	v_mfma_f32_32x32x16_bf16 v[48:63], v[140:143], v[120:123], v[48:63]
	ds_read_b64_tr_b16 v[140:141], v0 offset:13312
	ds_read_b64_tr_b16 v[142:143], v0 offset:13824
	ds_read_b64_tr_b16 v[136:137], v0 offset:14336
	ds_read_b64_tr_b16 v[138:139], v0 offset:14848
	ds_read_b64_tr_b16 v[132:133], v0 offset:15360
	ds_read_b64_tr_b16 v[134:135], v0 offset:15872
	ds_read_b64_tr_b16 v[128:129], v0 offset:16384
	ds_read_b64_tr_b16 v[130:131], v0 offset:16896
	ds_read_b64_tr_b16 v[124:125], v0 offset:17408
	ds_read_b64_tr_b16 v[126:127], v0 offset:17920
	ds_read_b64_tr_b16 v[10:11], v0 offset:18432
	ds_read_b64_tr_b16 v[12:13], v0 offset:18944
	ds_read_b64_tr_b16 v[6:7], v0 offset:19456
	ds_read_b64_tr_b16 v[8:9], v0 offset:19968
	ds_read_b64_tr_b16 v[2:3], v0 offset:20480
	ds_read_b64_tr_b16 v[4:5], v0 offset:20992
	s_cmp_gt_i32 s19, s84
	s_mov_b64 s[16:17], -1
	s_cbranch_scc1 .LBB0_1909
	v_max3_f32 v15, v64, s77, v65
	v_max3_f32 v15, v15, v66, v67
	v_max3_f32 v15, v15, v68, v69
	v_max3_f32 v15, v15, v70, v71
	v_max3_f32 v15, v15, v72, v73
	v_max3_f32 v15, v15, v74, v75
	v_max3_f32 v15, v15, v76, v77
	v_max3_f32 v15, v15, v78, v79
	v_max3_f32 v15, v15, v48, v49
	v_max3_f32 v15, v15, v50, v51
	v_max3_f32 v15, v15, v52, v53
	v_max3_f32 v15, v15, v54, v55
	v_max3_f32 v15, v15, v56, v57
	v_max3_f32 v15, v15, v58, v59
	v_max3_f32 v15, v15, v60, v61
	v_max3_f32 v15, v15, v62, v63
	s_mov_b64 s[16:17], 0

.LBB0_1911:
	v_and_b32_e32 v203, 64, v163
	v_xor_b32_e32 v202, 32, v163
	v_add_u32_e32 v203, 64, v203
	v_cmp_lt_i32_e32 vcc, v202, v203
	v_max_f32_e32 v203, v201, v201
	s_nop 0
	v_cndmask_b32_e32 v202, v163, v202, vcc
	v_lshlrev_b32_e32 v202, 2, v202
	ds_bpermute_b32 v202, v202, v15
	v_max_f32_e32 v15, v15, v15
	s_waitcnt lgkmcnt(0)
	v_max_f32_e32 v202, v202, v202
	v_max_f32_e32 v15, v15, v202
	v_mul_f32_e32 v15, 1.0, v15
	v_max_f32_e32 v15, v203, v15
	v_cmp_neq_f32_e32 vcc, s77, v15
	s_nop 1
	v_cndmask_b32_e32 v202, 0, v15, vcc
	v_fma_f32 v64, v64, s78, -v202
	v_exp_f32_e32 v203, v64
	v_fma_f32 v64, v65, s78, -v202
	v_exp_f32_e32 v65, v64
	v_fma_f32 v64, v66, s78, -v202
	v_exp_f32_e32 v66, v64
	v_fma_f32 v64, v67, s78, -v202
	v_exp_f32_e32 v67, v64
	v_fma_f32 v68, v68, s78, -v202
	v_add_f32_e32 v64, 0, v203
	v_exp_f32_e32 v68, v68
	v_fma_f32 v69, v69, s78, -v202
	v_fma_f32 v48, v48, s78, -v202
	v_add_f32_e32 v64, v65, v64
	v_exp_f32_e32 v69, v69
	v_fma_f32 v70, v70, s78, -v202
	v_exp_f32_e32 v205, v48
	v_fma_f32 v48, v49, s78, -v202
	v_add_f32_e32 v64, v66, v64
	v_exp_f32_e32 v70, v70
	v_fma_f32 v71, v71, s78, -v202
	v_exp_f32_e32 v206, v48
	v_fma_f32 v48, v50, s78, -v202
	v_add_f32_e32 v64, v67, v64
	v_exp_f32_e32 v71, v71
	v_fma_f32 v72, v72, s78, -v202
	v_exp_f32_e32 v207, v48
	v_fma_f32 v48, v51, s78, -v202
	v_add_f32_e32 v64, v68, v64
	v_exp_f32_e32 v72, v72
	v_fma_f32 v73, v73, s78, -v202
	v_exp_f32_e32 v208, v48
	v_fma_f32 v48, v52, s78, -v202
	v_add_f32_e32 v64, v69, v64
	v_exp_f32_e32 v73, v73
	v_fma_f32 v74, v74, s78, -v202
	v_exp_f32_e32 v209, v48
	v_fma_f32 v48, v53, s78, -v202
	v_add_f32_e32 v64, v70, v64
	v_exp_f32_e32 v74, v74
	v_fma_f32 v75, v75, s78, -v202
	v_exp_f32_e32 v210, v48
	v_fma_f32 v48, v54, s78, -v202
	v_add_f32_e32 v64, v71, v64
	v_exp_f32_e32 v75, v75
	v_fma_f32 v76, v76, s78, -v202
	v_exp_f32_e32 v211, v48
	v_fma_f32 v48, v55, s78, -v202
	v_add_f32_e32 v64, v72, v64
	v_exp_f32_e32 v76, v76
	v_fma_f32 v77, v77, s78, -v202
	v_exp_f32_e32 v212, v48
	v_fma_f32 v48, v56, s78, -v202
	v_add_f32_e32 v64, v73, v64
	v_exp_f32_e32 v77, v77
	v_fma_f32 v78, v78, s78, -v202
	v_exp_f32_e32 v213, v48
	v_fma_f32 v48, v57, s78, -v202
	v_add_f32_e32 v64, v74, v64
	v_exp_f32_e32 v78, v78
	v_fma_f32 v79, v79, s78, -v202
	v_exp_f32_e32 v214, v48
	v_fma_f32 v48, v58, s78, -v202
	v_add_f32_e32 v64, v75, v64
	v_exp_f32_e32 v79, v79
	v_exp_f32_e32 v215, v48
	v_fma_f32 v48, v59, s78, -v202
	v_add_f32_e32 v64, v76, v64
	v_exp_f32_e32 v216, v48
	v_fma_f32 v48, v60, s78, -v202
	v_add_f32_e32 v64, v77, v64
	v_exp_f32_e32 v217, v48
	v_fma_f32 v48, v61, s78, -v202
	v_sub_f32_e32 v201, v201, v202
	v_add_f32_e32 v64, v78, v64
	v_exp_f32_e32 v218, v48
	v_fma_f32 v48, v62, s78, -v202
	v_add_f32_e32 v204, v79, v64
	v_exp_f32_e32 v64, v201
	v_exp_f32_e32 v201, v48
	v_fma_f32 v48, v63, s78, -v202
	v_exp_f32_e32 v63, v48
	v_add_f32_e32 v48, v205, v204
	v_add_f32_e32 v48, v206, v48
	v_add_f32_e32 v48, v207, v48
	v_add_f32_e32 v48, v208, v48
	v_add_f32_e32 v48, v209, v48
	v_add_f32_e32 v48, v210, v48
	v_add_f32_e32 v48, v211, v48
	v_add_f32_e32 v48, v212, v48
	v_add_f32_e32 v48, v213, v48
	v_add_f32_e32 v48, v214, v48
	v_add_f32_e32 v48, v215, v48
	v_add_f32_e32 v48, v216, v48
	v_add_f32_e32 v48, v217, v48
	v_add_f32_e32 v48, v218, v48
	v_pk_mul_f32 v[46:47], v[46:47], v[64:65] op_sel_hi:[1,0]
	v_pk_mul_f32 v[44:45], v[44:45], v[64:65] op_sel_hi:[1,0]
	v_pk_mul_f32 v[42:43], v[42:43], v[64:65] op_sel_hi:[1,0]
	v_pk_mul_f32 v[40:41], v[40:41], v[64:65] op_sel_hi:[1,0]
	v_pk_mul_f32 v[38:39], v[38:39], v[64:65] op_sel_hi:[1,0]
	v_pk_mul_f32 v[36:37], v[36:37], v[64:65] op_sel_hi:[1,0]
	v_pk_mul_f32 v[34:35], v[34:35], v[64:65] op_sel_hi:[1,0]
	v_pk_mul_f32 v[32:33], v[32:33], v[64:65] op_sel_hi:[1,0]
	v_pk_mul_f32 v[30:31], v[30:31], v[64:65] op_sel_hi:[1,0]
	v_pk_mul_f32 v[28:29], v[28:29], v[64:65] op_sel_hi:[1,0]
	v_pk_mul_f32 v[26:27], v[26:27], v[64:65] op_sel_hi:[1,0]
	v_pk_mul_f32 v[24:25], v[24:25], v[64:65] op_sel_hi:[1,0]
	v_pk_mul_f32 v[22:23], v[22:23], v[64:65] op_sel_hi:[1,0]
	v_pk_mul_f32 v[20:21], v[20:21], v[64:65] op_sel_hi:[1,0]
	v_pk_mul_f32 v[18:19], v[18:19], v[64:65] op_sel_hi:[1,0]
	v_pk_mul_f32 v[16:17], v[16:17], v[64:65] op_sel_hi:[1,0]
	v_add_f32_e32 v48, v201, v48
	v_add_f32_e32 v202, v63, v48
	v_cvt_pk_bf16_f32 v48, v203, v65
	v_cvt_pk_bf16_f32 v49, v66, v67
	v_cvt_pk_bf16_f32 v50, v68, v69
	v_cvt_pk_bf16_f32 v51, v70, v71
	v_cvt_pk_bf16_f32 v52, v72, v73
	v_cvt_pk_bf16_f32 v53, v74, v75
	v_cvt_pk_bf16_f32 v54, v76, v77
	v_cvt_pk_bf16_f32 v55, v78, v79
	v_cvt_pk_bf16_f32 v56, v205, v206
	v_cvt_pk_bf16_f32 v57, v207, v208
	v_cvt_pk_bf16_f32 v58, v209, v210
	v_cvt_pk_bf16_f32 v59, v211, v212
	v_cvt_pk_bf16_f32 v60, v213, v214
	v_cvt_pk_bf16_f32 v61, v215, v216
	v_cvt_pk_bf16_f32 v62, v217, v218
	v_cvt_pk_bf16_f32 v63, v201, v63
	v_mfma_f32_32x32x16_bf16 v[32:47], v[140:143], v[48:51], v[32:47]
	v_fmac_f32_e32 v202, v200, v64
	v_mov_b32_e32 v201, v15
	v_mov_b32_e32 v200, v202
	v_mfma_f32_32x32x16_bf16 v[16:31], v[124:127], v[48:51], v[16:31]
	v_mfma_f32_32x32x16_bf16 v[32:47], v[136:139], v[52:55], v[32:47]
	v_mfma_f32_32x32x16_bf16 v[16:31], v[10:13], v[52:55], v[16:31]
	v_mfma_f32_32x32x16_bf16 v[32:47], v[132:135], v[56:59], v[32:47]
	v_mfma_f32_32x32x16_bf16 v[16:31], v[6:9], v[56:59], v[16:31]
	v_mfma_f32_32x32x16_bf16 v[32:47], v[128:131], v[60:63], v[32:47]
	v_mfma_f32_32x32x16_bf16 v[16:31], v[2:5], v[60:63], v[16:31]
	s_add_i32 s0, s19, 1
	s_cmp_gt_i32 s0, s85
	s_cbranch_scc0 .LBB0_1914

.LBB0_1918:
	v_and_b32_e32 v15, 64, v163
	v_xor_b32_e32 v14, 32, v163
	v_add_u32_e32 v15, 64, v15
	v_cmp_lt_i32_e32 vcc, v14, v15
	v_max_f32_e32 v15, v201, v201
	s_nop 0
	v_cndmask_b32_e32 v14, v163, v14, vcc
	v_lshlrev_b32_e32 v14, 2, v14
	ds_bpermute_b32 v14, v14, v0
	v_max_f32_e32 v0, v0, v0
	s_waitcnt lgkmcnt(0)
	v_max_f32_e32 v14, v14, v14
	v_max_f32_e32 v0, v0, v14
	v_mul_f32_e32 v0, 1.0, v0
	v_max_f32_e32 v14, v15, v0
	v_cmp_neq_f32_e32 vcc, s77, v14
	s_nop 1
	v_cndmask_b32_e32 v15, 0, v14, vcc
	v_fma_f32 v64, v64, s78, -v15
	v_exp_f32_e32 v64, v64
	v_fma_f32 v65, v65, s78, -v15
	v_exp_f32_e32 v65, v65
	v_fma_f32 v66, v66, s78, -v15
	v_exp_f32_e32 v66, v66
	v_fma_f32 v67, v67, s78, -v15
	v_exp_f32_e32 v67, v67
	v_fma_f32 v68, v68, s78, -v15
	v_sub_f32_e32 v0, v201, v15
	v_add_f32_e32 v201, 0, v64
	v_exp_f32_e32 v68, v68
	v_fma_f32 v69, v69, s78, -v15
	v_add_f32_e32 v201, v65, v201
	v_exp_f32_e32 v69, v69
	v_fma_f32 v70, v70, s78, -v15
	v_fma_f32 v48, v48, s78, -v15
	v_add_f32_e32 v201, v66, v201
	v_exp_f32_e32 v70, v70
	v_fma_f32 v71, v71, s78, -v15
	v_exp_f32_e32 v202, v48
	v_fma_f32 v48, v49, s78, -v15
	v_add_f32_e32 v201, v67, v201
	v_exp_f32_e32 v71, v71
	v_fma_f32 v72, v72, s78, -v15
	v_exp_f32_e32 v203, v48
	v_fma_f32 v48, v50, s78, -v15
	v_add_f32_e32 v201, v68, v201
	v_exp_f32_e32 v72, v72
	v_fma_f32 v73, v73, s78, -v15
	v_exp_f32_e32 v204, v48
	v_fma_f32 v48, v51, s78, -v15
	v_add_f32_e32 v201, v69, v201
	v_exp_f32_e32 v73, v73
	v_fma_f32 v74, v74, s78, -v15
	v_exp_f32_e32 v205, v48
	v_fma_f32 v48, v52, s78, -v15
	v_add_f32_e32 v201, v70, v201
	v_exp_f32_e32 v74, v74
	v_fma_f32 v75, v75, s78, -v15
	v_exp_f32_e32 v206, v48
	v_fma_f32 v48, v53, s78, -v15
	v_add_f32_e32 v201, v71, v201
	v_exp_f32_e32 v75, v75
	v_fma_f32 v76, v76, s78, -v15
	v_exp_f32_e32 v207, v48
	v_fma_f32 v48, v54, s78, -v15
	v_add_f32_e32 v201, v72, v201
	v_exp_f32_e32 v76, v76
	v_fma_f32 v77, v77, s78, -v15
	v_exp_f32_e32 v208, v48
	v_fma_f32 v48, v55, s78, -v15
	v_add_f32_e32 v201, v73, v201
	v_exp_f32_e32 v77, v77
	v_fma_f32 v78, v78, s78, -v15
	v_exp_f32_e32 v209, v48
	v_fma_f32 v48, v56, s78, -v15
	v_add_f32_e32 v201, v74, v201
	v_exp_f32_e32 v78, v78
	v_fma_f32 v79, v79, s78, -v15
	v_exp_f32_e32 v210, v48
	v_fma_f32 v48, v57, s78, -v15
	v_add_f32_e32 v201, v75, v201
	v_exp_f32_e32 v79, v79
	v_exp_f32_e32 v211, v48
	v_fma_f32 v48, v58, s78, -v15
	v_add_f32_e32 v201, v76, v201
	v_exp_f32_e32 v212, v48
	v_fma_f32 v48, v59, s78, -v15
	v_add_f32_e32 v201, v77, v201
	v_exp_f32_e32 v213, v48
	v_fma_f32 v48, v60, s78, -v15
	v_add_f32_e32 v201, v78, v201
	v_exp_f32_e32 v214, v48
	v_fma_f32 v48, v61, s78, -v15
	v_add_f32_e32 v201, v79, v201
	v_exp_f32_e32 v215, v48
	v_fma_f32 v48, v62, s78, -v15
	v_exp_f32_e32 v216, v48
	v_add_f32_e32 v48, v202, v201
	v_add_f32_e32 v48, v203, v48
	v_add_f32_e32 v48, v204, v48
	v_add_f32_e32 v48, v205, v48
	v_add_f32_e32 v48, v206, v48
	v_add_f32_e32 v48, v207, v48
	v_add_f32_e32 v48, v208, v48
	v_add_f32_e32 v48, v209, v48
	v_add_f32_e32 v48, v210, v48
	v_add_f32_e32 v48, v211, v48
	v_exp_f32_e32 v0, v0
	v_fma_f32 v15, v63, s78, -v15
	v_add_f32_e32 v48, v212, v48
	v_exp_f32_e32 v15, v15
	v_add_f32_e32 v48, v213, v48
	v_add_f32_e32 v48, v214, v48
	v_add_f32_e32 v48, v215, v48
	v_pk_mul_f32 v[46:47], v[46:47], v[0:1] op_sel_hi:[1,0]
	v_pk_mul_f32 v[44:45], v[44:45], v[0:1] op_sel_hi:[1,0]
	v_pk_mul_f32 v[42:43], v[42:43], v[0:1] op_sel_hi:[1,0]
	v_pk_mul_f32 v[40:41], v[40:41], v[0:1] op_sel_hi:[1,0]
	v_pk_mul_f32 v[38:39], v[38:39], v[0:1] op_sel_hi:[1,0]
	v_pk_mul_f32 v[36:37], v[36:37], v[0:1] op_sel_hi:[1,0]
	v_pk_mul_f32 v[34:35], v[34:35], v[0:1] op_sel_hi:[1,0]
	v_pk_mul_f32 v[32:33], v[32:33], v[0:1] op_sel_hi:[1,0]
	v_pk_mul_f32 v[30:31], v[30:31], v[0:1] op_sel_hi:[1,0]
	v_pk_mul_f32 v[28:29], v[28:29], v[0:1] op_sel_hi:[1,0]
	v_pk_mul_f32 v[26:27], v[26:27], v[0:1] op_sel_hi:[1,0]
	v_pk_mul_f32 v[24:25], v[24:25], v[0:1] op_sel_hi:[1,0]
	v_pk_mul_f32 v[22:23], v[22:23], v[0:1] op_sel_hi:[1,0]
	v_pk_mul_f32 v[20:21], v[20:21], v[0:1] op_sel_hi:[1,0]
	v_pk_mul_f32 v[18:19], v[18:19], v[0:1] op_sel_hi:[1,0]
	v_pk_mul_f32 v[16:17], v[16:17], v[0:1] op_sel_hi:[1,0]
	v_add_f32_e32 v48, v216, v48
	v_add_f32_e32 v217, v15, v48
	v_cvt_pk_bf16_f32 v48, v64, v65
	v_cvt_pk_bf16_f32 v49, v66, v67
	v_cvt_pk_bf16_f32 v50, v68, v69
	v_cvt_pk_bf16_f32 v51, v70, v71
	v_cvt_pk_bf16_f32 v52, v72, v73
	v_cvt_pk_bf16_f32 v53, v74, v75
	v_cvt_pk_bf16_f32 v54, v76, v77
	v_cvt_pk_bf16_f32 v55, v78, v79
	v_cvt_pk_bf16_f32 v56, v202, v203
	v_cvt_pk_bf16_f32 v57, v204, v205
	v_cvt_pk_bf16_f32 v58, v206, v207
	v_cvt_pk_bf16_f32 v59, v208, v209
	v_cvt_pk_bf16_f32 v60, v210, v211
	v_cvt_pk_bf16_f32 v61, v212, v213
	v_cvt_pk_bf16_f32 v62, v214, v215
	v_cvt_pk_bf16_f32 v63, v216, v15
	v_mfma_f32_32x32x16_bf16 v[32:47], v[140:143], v[48:51], v[32:47]
	v_fmac_f32_e32 v217, v200, v0
	v_mov_b32_e32 v201, v14
	v_mov_b32_e32 v200, v217
	v_mfma_f32_32x32x16_bf16 v[16:31], v[124:127], v[48:51], v[16:31]
	v_mfma_f32_32x32x16_bf16 v[32:47], v[136:139], v[52:55], v[32:47]
	v_mfma_f32_32x32x16_bf16 v[16:31], v[10:13], v[52:55], v[16:31]
	v_mfma_f32_32x32x16_bf16 v[32:47], v[132:135], v[56:59], v[32:47]
	v_mfma_f32_32x32x16_bf16 v[16:31], v[6:9], v[56:59], v[16:31]
	v_mfma_f32_32x32x16_bf16 v[32:47], v[128:131], v[60:63], v[32:47]
	v_mfma_f32_32x32x16_bf16 v[16:31], v[2:5], v[60:63], v[16:31]
	s_xor_b32 s18, s18, 1
	s_and_b64 vcc, exec, s[14:15]
	s_cbranch_vccz .LBB0_1883

	.amdhsa_kernel _Z8mega_fwd6Params
		.amdhsa_group_segment_fixed_size 0
		.amdhsa_private_segment_fixed_size 0
		.amdhsa_kernarg_size 400
		.amdhsa_user_sgpr_count 2
		.amdhsa_user_sgpr_dispatch_ptr 0
		.amdhsa_user_sgpr_queue_ptr 0
		.amdhsa_user_sgpr_kernarg_segment_ptr 1
		.amdhsa_user_sgpr_dispatch_id 0
		.amdhsa_user_sgpr_kernarg_preload_length 0
		.amdhsa_user_sgpr_kernarg_preload_offset 0
		.amdhsa_user_sgpr_private_segment_size 0
		.amdhsa_uses_dynamic_stack 0
		.amdhsa_enable_private_segment 0
		.amdhsa_system_sgpr_workgroup_id_x 1
		.amdhsa_system_sgpr_workgroup_id_y 0
		.amdhsa_system_sgpr_workgroup_id_z 0
		.amdhsa_system_sgpr_workgroup_info 0
		.amdhsa_system_vgpr_workitem_id 2
		.amdhsa_next_free_vgpr 256
		.amdhsa_next_free_sgpr 100
		.amdhsa_accum_offset 256
		.amdhsa_reserve_vcc 1
		.amdhsa_float_round_mode_32 0
		.amdhsa_float_round_mode_16_64 0
		.amdhsa_float_denorm_mode_32 3
		.amdhsa_float_denorm_mode_16_64 3
		.amdhsa_dx10_clamp 1
		.amdhsa_ieee_mode 1
		.amdhsa_fp16_overflow 0
		.amdhsa_tg_split 0
		.amdhsa_exception_fp_ieee_invalid_op 0
		.amdhsa_exception_fp_denorm_src 0
		.amdhsa_exception_fp_ieee_div_zero 0
		.amdhsa_exception_fp_ieee_overflow 0
		.amdhsa_exception_fp_ieee_underflow 0
		.amdhsa_exception_fp_ieee_inexact 0
		.amdhsa_exception_int_div_zero 0
	.end_amdhsa_kernel

amdhsa.kernels:
  - .agpr_count:     0
    .args:
      - .offset:         0
        .size:           144
        .value_kind:     by_value
      - .offset:         144
        .size:           4
        .value_kind:     hidden_block_count_x
      - .offset:         148
        .size:           4
        .value_kind:     hidden_block_count_y
      - .offset:         152
        .size:           4
        .value_kind:     hidden_block_count_z
      - .offset:         156
        .size:           2
        .value_kind:     hidden_group_size_x
      - .offset:         158
        .size:           2
        .value_kind:     hidden_group_size_y
      - .offset:         160
        .size:           2
        .value_kind:     hidden_group_size_z
      - .offset:         162
        .size:           2
        .value_kind:     hidden_remainder_x
      - .offset:         164
        .size:           2
        .value_kind:     hidden_remainder_y
      - .offset:         166
        .size:           2
        .value_kind:     hidden_remainder_z
      - .offset:         184
        .size:           8
        .value_kind:     hidden_global_offset_x
      - .offset:         192
        .size:           8
        .value_kind:     hidden_global_offset_y
      - .offset:         200
        .size:           8
        .value_kind:     hidden_global_offset_z
      - .offset:         208
        .size:           2
        .value_kind:     hidden_grid_dims
      - .offset:         232
        .size:           8
        .value_kind:     hidden_multigrid_sync_arg
      - .offset:         264
        .size:           4
        .value_kind:     hidden_dynamic_lds_size
    .group_segment_fixed_size: 0
    .kernarg_segment_align: 8
    .kernarg_segment_size: 400
    .language:       OpenCL C
    .language_version:
      - 2
      - 0
    .max_flat_workgroup_size: 512
    .name:           _Z8mega_fwd6Params
    .private_segment_fixed_size: 0
    .sgpr_count:     106
    .sgpr_spill_count: 56
    .symbol:         _Z8mega_fwd6Params.kd
    .uniform_work_group_size: 1
    .uses_dynamic_stack: false
    .vgpr_count:     256
    .vgpr_spill_count: 0
    .wavefront_size: 64
